# P2 epilogue: row-statistics shuffles by permlane16/32 swaps instead of ds_bpermute
# speedup vs baseline: 1.0023x; 1.0023x over previous
;     __device__ __forceinline__ void operator()(const f32x4 (&acc)[2][2][4][2], const Unit& u, int wr, int wc, int fr, int fq) const {
;     ...
;         for (int mh = 0; mh < 2; ++mh) {
;             f32x4 bf[2][2][2]; u32x4 bh[2][2];
; #pragma unroll
;             for (int m2 = 0; m2 < 2; ++m2)
; #pragma unroll
;                 for (int bj = 0; bj < 2; ++bj) {
;                     const size_t off = (size_t)(u.pm * BM + ai * HALF + wr * 64 + (2 * mh + m2) * 16 + fr) * 1024 + col0 + bj * HALF;
;                     if (!basef) bh[m2][bj] = *(const u32x4*)(xin + off);
;                 }
; #pragma unroll
;             for (int m2 = 0; m2 < 2; ++m2) {
;                 const int m = 2 * mh + m2;
;                 const int row = u.pm * BM + ai * HALF + wr * 64 + m * 16 + fr; float sq = 0.f;
;                 if (basef) {
; #pragma unroll
;                     for (int bj = 0; bj < 2; ++bj) { const size_t off = (size_t)row * 1024 + col0 + bj * HALF; bf[m2][bj][0] = *(const f32x4*)(basef + off); bf[m2][bj][1] = *(const f32x4*)(basef + off + 4); }
;                 }
; #pragma unroll
;                 for (int bj = 0; bj < 2; ++bj) {
;                     const size_t off = (size_t)row * 1024 + col0 + bj * HALF;
;                     float bv[8];
;                     if (basef) { const f32x4 b0 = bf[m2][bj][0], b1 = bf[m2][bj][1]; bv[0] = b0[0]; bv[1] = b0[1]; bv[2] = b0[2]; bv[3] = b0[3]; bv[4] = b1[0]; bv[5] = b1[1]; bv[6] = b1[2]; bv[7] = b1[3]; }
;                     else { const u32x4 gw = bh[m2][bj];
;                         bv[0] = __uint_as_float(gw.x << 16); bv[1] = __uint_as_float(gw.x & 0xffff0000u); bv[2] = __uint_as_float(gw.y << 16); bv[3] = __uint_as_float(gw.y & 0xffff0000u);
;                         bv[4] = __uint_as_float(gw.z << 16); bv[5] = __uint_as_float(gw.z & 0xffff0000u); bv[6] = __uint_as_float(gw.w << 16); bv[7] = __uint_as_float(gw.w & 0xffff0000u); }
;                     float y[8];
; #pragma unroll
;                     for (int e = 0; e < 4; ++e) { y[e] = bv[e] + alpha * acc[ai][bj][m][0][e]; y[4 + e] = bv[4 + e] + alpha * acc[ai][bj][m][1][e]; }
;                     u32x4 w; w.x = cvt_pk_bf16(y[0], y[1]); w.y = cvt_pk_bf16(y[2], y[3]); w.z = cvt_pk_bf16(y[4], y[5]); w.w = cvt_pk_bf16(y[6], y[7]);
;                     *(u32x4*)(xs + off) = w;
.LBB0_1461:
	v_readlane_b32 s70, v253, 17
	v_readlane_b32 s71, v253, 18
	v_readlane_b32 s50, v253, 13
	v_readlane_b32 s51, v253, 14
	s_mov_b32 s99, 0
	v_lshl_or_b32 v246, s67, 8, v200
	v_lshl_add_u32 v247, s68, 8, v196
	v_mov_b32_e32 v235, 0
	v_lshlrev_b32_e32 v234, 2, v246
	v_lshl_add_u32 v234, v247, 12, v234
	v_lshl_add_u64 v[234:235], s[4:5], 0, v[234:235]
	s_mov_b32 s98, 0x0
	v_lshl_add_u64 v[240:241], v[234:235], 0, s[98:99]
	global_load_dwordx4 v[0:3], v[240:241], off
	global_load_dwordx4 v[4:7], v[240:241], off offset:16
	global_load_dwordx4 v[8:11], v[240:241], off offset:512
	global_load_dwordx4 v[12:15], v[240:241], off offset:528
	s_mov_b32 s98, 0x10000
	v_lshl_add_u64 v[240:241], v[234:235], 0, s[98:99]
	global_load_dwordx4 v[16:19], v[240:241], off
	global_load_dwordx4 v[20:23], v[240:241], off offset:16
	global_load_dwordx4 v[104:107], v[240:241], off offset:512
	global_load_dwordx4 v[116:119], v[240:241], off offset:528
	s_mov_b32 s98, 0x20000
	v_lshl_add_u64 v[240:241], v[234:235], 0, s[98:99]
	global_load_dwordx4 v[184:187], v[240:241], off
	global_load_dwordx4 v[188:191], v[240:241], off offset:16
	global_load_dwordx4 v[192:195], v[240:241], off offset:512
	global_load_dwordx4 v[206:209], v[240:241], off offset:528
	s_mov_b32 s98, 0x30000
	v_lshl_add_u64 v[240:241], v[234:235], 0, s[98:99]
	global_load_dwordx4 v[210:213], v[240:241], off
	global_load_dwordx4 v[214:217], v[240:241], off offset:16
	global_load_dwordx4 v[132:135], v[240:241], off offset:512
	global_load_dwordx4 v[124:127], v[240:241], off offset:528
	v_mov_b32_e32 v237, 0
	v_lshlrev_b32_e32 v236, 1, v246
	v_lshl_add_u32 v236, v247, 11, v236
	v_lshl_add_u64 v[236:237], s[50:51], 0, v[236:237]
	v_bfe_u32 v238, v198, 6, 2
	v_lshlrev_b32_e32 v238, 2, v238
	v_lshl_add_u32 v238, s67, 4, v238
	v_mov_b32_e32 v239, 0
	v_lshl_add_u32 v238, v247, 6, v238
	v_lshl_add_u64 v[238:239], s[0:1], 0, v[238:239]
	v_xor_b32_e32 v242, 16, v204
	v_xor_b32_e32 v243, 32, v204
	v_lshlrev_b32_e32 v242, 2, v242
	v_lshlrev_b32_e32 v243, 2, v243
	s_waitcnt vmcnt(12)
	v_fmac_f32_e32 v0, 0.5, v28
	v_fmac_f32_e32 v1, 0.5, v29
	v_fmac_f32_e32 v2, 0.5, v30
	v_fmac_f32_e32 v3, 0.5, v31
	v_fmac_f32_e32 v4, 0.5, v24
	v_fmac_f32_e32 v5, 0.5, v25
	v_fmac_f32_e32 v6, 0.5, v26
	v_fmac_f32_e32 v7, 0.5, v27
	v_fmac_f32_e32 v8, 0.5, v36
	v_fmac_f32_e32 v9, 0.5, v37
	v_fmac_f32_e32 v10, 0.5, v38
	v_fmac_f32_e32 v11, 0.5, v39
	v_fmac_f32_e32 v12, 0.5, v32
	v_fmac_f32_e32 v13, 0.5, v33
	v_fmac_f32_e32 v14, 0.5, v34
	v_fmac_f32_e32 v15, 0.5, v35
	v_mul_f32_e32 v24, v0, v0
	v_mul_f32_e32 v25, v2, v2
	v_mul_f32_e32 v26, v4, v4
	v_mul_f32_e32 v27, v6, v6
	v_fmac_f32_e32 v24, v1, v1
	v_fmac_f32_e32 v25, v3, v3
	v_fmac_f32_e32 v26, v5, v5
	v_fmac_f32_e32 v27, v7, v7
	v_add_f32_e32 v24, v24, v25
	v_add_f32_e32 v26, v26, v27
	v_add_f32_e32 v24, v24, v26
	v_mul_f32_e32 v32, v8, v8
	v_mul_f32_e32 v33, v10, v10
	v_mul_f32_e32 v34, v12, v12
	v_mul_f32_e32 v35, v14, v14
	v_fmac_f32_e32 v32, v9, v9
	v_fmac_f32_e32 v33, v11, v11
	v_fmac_f32_e32 v34, v13, v13
	v_fmac_f32_e32 v35, v15, v15
	v_add_f32_e32 v32, v32, v33
	v_add_f32_e32 v34, v34, v35
	v_add_f32_e32 v32, v32, v34
	v_add_f32_e32 v244, v24, v32
	v_mov_b32_e32 v245, v244
	s_nop 1
	v_permlane16_swap_b32_e32 v244, v245
	s_mov_b32 s98, 0x0
	v_lshl_add_u64 v[240:241], v[236:237], 0, s[98:99]
	v_cvt_pk_bf16_f32 v28, v0, v1
	v_cvt_pk_bf16_f32 v29, v2, v3
	v_cvt_pk_bf16_f32 v30, v4, v5
	v_cvt_pk_bf16_f32 v31, v6, v7
	global_store_dwordx4 v[240:241], v[28:31], off
	v_cvt_pk_bf16_f32 v36, v8, v9
	v_cvt_pk_bf16_f32 v37, v10, v11
	v_cvt_pk_bf16_f32 v38, v12, v13
	v_cvt_pk_bf16_f32 v39, v14, v15
	global_store_dwordx4 v[240:241], v[36:39], off offset:256
	s_waitcnt lgkmcnt(0)
	v_add_f32_e32 v244, v244, v245
	v_mov_b32_e32 v245, v244
	s_nop 1
	v_permlane32_swap_b32_e32 v244, v245
	s_mov_b32 s98, 0x0
	v_lshl_add_u64 v[240:241], v[238:239], 0, s[98:99]
	s_waitcnt lgkmcnt(0)
	v_add_f32_e32 v244, v244, v245
	s_and_saveexec_b64 s[50:51], s[8:9]
	global_store_dword v[240:241], v244, off
	s_mov_b64 exec, s[50:51]
	s_mov_b32 s98, 0x80000
	v_lshl_add_u64 v[240:241], v[234:235], 0, s[98:99]
	global_load_dwordx4 v[0:3], v[240:241], off
	global_load_dwordx4 v[4:7], v[240:241], off offset:16
	global_load_dwordx4 v[8:11], v[240:241], off offset:512
	global_load_dwordx4 v[12:15], v[240:241], off offset:528
	s_waitcnt vmcnt(15)
	v_fmac_f32_e32 v16, 0.5, v44
	v_fmac_f32_e32 v17, 0.5, v45
	v_fmac_f32_e32 v18, 0.5, v46
	v_fmac_f32_e32 v19, 0.5, v47
	v_fmac_f32_e32 v20, 0.5, v40
	v_fmac_f32_e32 v21, 0.5, v41
	v_fmac_f32_e32 v22, 0.5, v42
	v_fmac_f32_e32 v23, 0.5, v43
	v_fmac_f32_e32 v104, 0.5, v164
	v_fmac_f32_e32 v105, 0.5, v165
	v_fmac_f32_e32 v106, 0.5, v166
	v_fmac_f32_e32 v107, 0.5, v167
	v_fmac_f32_e32 v116, 0.5, v160
	v_fmac_f32_e32 v117, 0.5, v161
	v_fmac_f32_e32 v118, 0.5, v162
	v_fmac_f32_e32 v119, 0.5, v163
	v_mul_f32_e32 v40, v16, v16
	v_mul_f32_e32 v41, v18, v18
	v_mul_f32_e32 v42, v20, v20
	v_mul_f32_e32 v43, v22, v22
	v_fmac_f32_e32 v40, v17, v17
	v_fmac_f32_e32 v41, v19, v19
	v_fmac_f32_e32 v42, v21, v21
	v_fmac_f32_e32 v43, v23, v23
	v_add_f32_e32 v40, v40, v41
	v_add_f32_e32 v42, v42, v43
	v_add_f32_e32 v40, v40, v42
	v_mul_f32_e32 v160, v104, v104
	v_mul_f32_e32 v161, v106, v106
	v_mul_f32_e32 v162, v116, v116
	v_mul_f32_e32 v163, v118, v118
	v_fmac_f32_e32 v160, v105, v105
	v_fmac_f32_e32 v161, v107, v107
	v_fmac_f32_e32 v162, v117, v117
	v_fmac_f32_e32 v163, v119, v119
	v_add_f32_e32 v160, v160, v161
	v_add_f32_e32 v162, v162, v163
	v_add_f32_e32 v160, v160, v162
	v_add_f32_e32 v244, v40, v160
	v_mov_b32_e32 v245, v244
	s_nop 1
	v_permlane16_swap_b32_e32 v244, v245
	s_mov_b32 s98, 0x8000
	v_lshl_add_u64 v[240:241], v[236:237], 0, s[98:99]
	v_cvt_pk_bf16_f32 v44, v16, v17
	v_cvt_pk_bf16_f32 v45, v18, v19
	v_cvt_pk_bf16_f32 v46, v20, v21
	v_cvt_pk_bf16_f32 v47, v22, v23
	global_store_dwordx4 v[240:241], v[44:47], off
	v_cvt_pk_bf16_f32 v164, v104, v105
	v_cvt_pk_bf16_f32 v165, v106, v107
	v_cvt_pk_bf16_f32 v166, v116, v117
	v_cvt_pk_bf16_f32 v167, v118, v119
	global_store_dwordx4 v[240:241], v[164:167], off offset:256
	s_waitcnt lgkmcnt(0)
;     __device__ __forceinline__ void operator()(const f32x4 (&acc)[2][2][4][2], const Unit& u, int wr, int wc, int fr, int fq) const {
;     ...
;         for (int mh = 0; mh < 2; ++mh) {
;             f32x4 bf[2][2][2]; u32x4 bh[2][2];
; #pragma unroll
;             for (int m2 = 0; m2 < 2; ++m2)
; #pragma unroll
;                 for (int bj = 0; bj < 2; ++bj) {
;                     const size_t off = (size_t)(u.pm * BM + ai * HALF + wr * 64 + (2 * mh + m2) * 16 + fr) * 1024 + col0 + bj * HALF;
;                     if (!basef) bh[m2][bj] = *(const u32x4*)(xin + off);
;                 }
; #pragma unroll
;             for (int m2 = 0; m2 < 2; ++m2) {
;                 const int m = 2 * mh + m2;
;                 const int row = u.pm * BM + ai * HALF + wr * 64 + m * 16 + fr; float sq = 0.f;
;                 if (basef) {
; #pragma unroll
;                     for (int bj = 0; bj < 2; ++bj) { const size_t off = (size_t)row * 1024 + col0 + bj * HALF; bf[m2][bj][0] = *(const f32x4*)(basef + off); bf[m2][bj][1] = *(const f32x4*)(basef + off + 4); }
;                 }
; #pragma unroll
;                 for (int bj = 0; bj < 2; ++bj) {
;                     const size_t off = (size_t)row * 1024 + col0 + bj * HALF;
;                     float bv[8];
;                     if (basef) { const f32x4 b0 = bf[m2][bj][0], b1 = bf[m2][bj][1]; bv[0] = b0[0]; bv[1] = b0[1]; bv[2] = b0[2]; bv[3] = b0[3]; bv[4] = b1[0]; bv[5] = b1[1]; bv[6] = b1[2]; bv[7] = b1[3]; }
;                     else { const u32x4 gw = bh[m2][bj];
;                         bv[0] = __uint_as_float(gw.x << 16); bv[1] = __uint_as_float(gw.x & 0xffff0000u); bv[2] = __uint_as_float(gw.y << 16); bv[3] = __uint_as_float(gw.y & 0xffff0000u);
;                         bv[4] = __uint_as_float(gw.z << 16); bv[5] = __uint_as_float(gw.z & 0xffff0000u); bv[6] = __uint_as_float(gw.w << 16); bv[7] = __uint_as_float(gw.w & 0xffff0000u); }
;                     float y[8];
; #pragma unroll
;                     for (int e = 0; e < 4; ++e) { y[e] = bv[e] + alpha * acc[ai][bj][m][0][e]; y[4 + e] = bv[4 + e] + alpha * acc[ai][bj][m][1][e]; }
;                     u32x4 w; w.x = cvt_pk_bf16(y[0], y[1]); w.y = cvt_pk_bf16(y[2], y[3]); w.z = cvt_pk_bf16(y[4], y[5]); w.w = cvt_pk_bf16(y[6], y[7]);
;                     *(u32x4*)(xs + off) = w;
	v_add_f32_e32 v244, v244, v245
	v_mov_b32_e32 v245, v244
	s_nop 1
	v_permlane32_swap_b32_e32 v244, v245
	s_mov_b32 s98, 0x400
	v_lshl_add_u64 v[240:241], v[238:239], 0, s[98:99]
	s_waitcnt lgkmcnt(0)
	v_add_f32_e32 v244, v244, v245
	s_and_saveexec_b64 s[50:51], s[8:9]
	global_store_dword v[240:241], v244, off
	s_mov_b64 exec, s[50:51]
	s_mov_b32 s98, 0x90000
	v_lshl_add_u64 v[240:241], v[234:235], 0, s[98:99]
	global_load_dwordx4 v[16:19], v[240:241], off
	global_load_dwordx4 v[20:23], v[240:241], off offset:16
	global_load_dwordx4 v[104:107], v[240:241], off offset:512
	global_load_dwordx4 v[116:119], v[240:241], off offset:528
	s_waitcnt vmcnt(18)
	v_fmac_f32_e32 v184, 0.5, v156
	v_fmac_f32_e32 v185, 0.5, v157
	v_fmac_f32_e32 v186, 0.5, v158
	v_fmac_f32_e32 v187, 0.5, v159
	v_fmac_f32_e32 v188, 0.5, v152
	v_fmac_f32_e32 v189, 0.5, v153
	v_fmac_f32_e32 v190, 0.5, v154
	v_fmac_f32_e32 v191, 0.5, v155
	v_fmac_f32_e32 v192, 0.5, v148
	v_fmac_f32_e32 v193, 0.5, v149
	v_fmac_f32_e32 v194, 0.5, v150
	v_fmac_f32_e32 v195, 0.5, v151
	v_fmac_f32_e32 v206, 0.5, v144
	v_fmac_f32_e32 v207, 0.5, v145
	v_fmac_f32_e32 v208, 0.5, v146
	v_fmac_f32_e32 v209, 0.5, v147
	v_mul_f32_e32 v152, v184, v184
	v_mul_f32_e32 v153, v186, v186
	v_mul_f32_e32 v154, v188, v188
	v_mul_f32_e32 v155, v190, v190
	v_fmac_f32_e32 v152, v185, v185
	v_fmac_f32_e32 v153, v187, v187
	v_fmac_f32_e32 v154, v189, v189
	v_fmac_f32_e32 v155, v191, v191
	v_add_f32_e32 v152, v152, v153
	v_add_f32_e32 v154, v154, v155
	v_add_f32_e32 v152, v152, v154
	v_mul_f32_e32 v144, v192, v192
	v_mul_f32_e32 v145, v194, v194
	v_mul_f32_e32 v146, v206, v206
	v_mul_f32_e32 v147, v208, v208
	v_fmac_f32_e32 v144, v193, v193
	v_fmac_f32_e32 v145, v195, v195
	v_fmac_f32_e32 v146, v207, v207
	v_fmac_f32_e32 v147, v209, v209
	v_add_f32_e32 v144, v144, v145
	v_add_f32_e32 v146, v146, v147
	v_add_f32_e32 v144, v144, v146
	v_add_f32_e32 v244, v152, v144
	v_mov_b32_e32 v245, v244
	s_nop 1
	v_permlane16_swap_b32_e32 v244, v245
	s_mov_b32 s98, 0x10000
	v_lshl_add_u64 v[240:241], v[236:237], 0, s[98:99]
	v_cvt_pk_bf16_f32 v156, v184, v185
	v_cvt_pk_bf16_f32 v157, v186, v187
	v_cvt_pk_bf16_f32 v158, v188, v189
	v_cvt_pk_bf16_f32 v159, v190, v191
	global_store_dwordx4 v[240:241], v[156:159], off
	v_cvt_pk_bf16_f32 v148, v192, v193
	v_cvt_pk_bf16_f32 v149, v194, v195
	v_cvt_pk_bf16_f32 v150, v206, v207
	v_cvt_pk_bf16_f32 v151, v208, v209
	global_store_dwordx4 v[240:241], v[148:151], off offset:256
	s_waitcnt lgkmcnt(0)
	v_add_f32_e32 v244, v244, v245
	v_mov_b32_e32 v245, v244
	s_nop 1
	v_permlane32_swap_b32_e32 v244, v245
	s_mov_b32 s98, 0x800
	v_lshl_add_u64 v[240:241], v[238:239], 0, s[98:99]
	s_waitcnt lgkmcnt(0)
	v_add_f32_e32 v244, v244, v245
	s_and_saveexec_b64 s[50:51], s[8:9]
	global_store_dword v[240:241], v244, off
	s_mov_b64 exec, s[50:51]
	s_mov_b32 s98, 0xa0000
	v_lshl_add_u64 v[240:241], v[234:235], 0, s[98:99]
	global_load_dwordx4 v[184:187], v[240:241], off
	global_load_dwordx4 v[188:191], v[240:241], off offset:16
	global_load_dwordx4 v[192:195], v[240:241], off offset:512
	global_load_dwordx4 v[206:209], v[240:241], off offset:528
	s_waitcnt vmcnt(21)
	v_fmac_f32_e32 v210, 0.5, v140
	v_fmac_f32_e32 v211, 0.5, v141
	v_fmac_f32_e32 v212, 0.5, v142
	v_fmac_f32_e32 v213, 0.5, v143
	v_fmac_f32_e32 v214, 0.5, v136
	v_fmac_f32_e32 v215, 0.5, v137
	v_fmac_f32_e32 v216, 0.5, v138
	v_fmac_f32_e32 v217, 0.5, v139
	v_fmac_f32_e32 v132, 0.5, v128
	v_fmac_f32_e32 v133, 0.5, v129
	v_fmac_f32_e32 v134, 0.5, v130
	v_fmac_f32_e32 v135, 0.5, v131
	v_fmac_f32_e32 v124, 0.5, v120
	v_fmac_f32_e32 v125, 0.5, v121
	v_fmac_f32_e32 v126, 0.5, v122
	v_fmac_f32_e32 v127, 0.5, v123
	v_mul_f32_e32 v136, v210, v210
	v_mul_f32_e32 v137, v212, v212
	v_mul_f32_e32 v138, v214, v214
	v_mul_f32_e32 v139, v216, v216
	v_fmac_f32_e32 v136, v211, v211
	v_fmac_f32_e32 v137, v213, v213
	v_fmac_f32_e32 v138, v215, v215
	v_fmac_f32_e32 v139, v217, v217
	v_add_f32_e32 v136, v136, v137
	v_add_f32_e32 v138, v138, v139
	v_add_f32_e32 v136, v136, v138
	v_mul_f32_e32 v120, v132, v132
	v_mul_f32_e32 v121, v134, v134
	v_mul_f32_e32 v122, v124, v124
	v_mul_f32_e32 v123, v126, v126
	v_fmac_f32_e32 v120, v133, v133
	v_fmac_f32_e32 v121, v135, v135
	v_fmac_f32_e32 v122, v125, v125
	v_fmac_f32_e32 v123, v127, v127
	v_add_f32_e32 v120, v120, v121
	v_add_f32_e32 v122, v122, v123
	v_add_f32_e32 v120, v120, v122
	v_add_f32_e32 v244, v136, v120
	v_mov_b32_e32 v245, v244
	s_nop 1
	v_permlane16_swap_b32_e32 v244, v245
	s_mov_b32 s98, 0x18000
	v_lshl_add_u64 v[240:241], v[236:237], 0, s[98:99]
	v_cvt_pk_bf16_f32 v140, v210, v211
	v_cvt_pk_bf16_f32 v141, v212, v213
	v_cvt_pk_bf16_f32 v142, v214, v215
	v_cvt_pk_bf16_f32 v143, v216, v217
	global_store_dwordx4 v[240:241], v[140:143], off
	v_cvt_pk_bf16_f32 v128, v132, v133
	v_cvt_pk_bf16_f32 v129, v134, v135
	v_cvt_pk_bf16_f32 v130, v124, v125
	v_cvt_pk_bf16_f32 v131, v126, v127
	global_store_dwordx4 v[240:241], v[128:131], off offset:256
	s_waitcnt lgkmcnt(0)
	v_add_f32_e32 v244, v244, v245
	v_mov_b32_e32 v245, v244
	s_nop 1
	v_permlane32_swap_b32_e32 v244, v245
	s_mov_b32 s98, 0xc00
	v_lshl_add_u64 v[240:241], v[238:239], 0, s[98:99]
	s_waitcnt lgkmcnt(0)
	v_add_f32_e32 v244, v244, v245
	s_and_saveexec_b64 s[50:51], s[8:9]
	global_store_dword v[240:241], v244, off
	s_mov_b64 exec, s[50:51]
	s_mov_b32 s98, 0xb0000
	v_lshl_add_u64 v[240:241], v[234:235], 0, s[98:99]
	global_load_dwordx4 v[210:213], v[240:241], off
	global_load_dwordx4 v[214:217], v[240:241], off offset:16
	global_load_dwordx4 v[132:135], v[240:241], off offset:512
	global_load_dwordx4 v[124:127], v[240:241], off offset:528
	s_waitcnt vmcnt(21)
;     __device__ __forceinline__ void operator()(const f32x4 (&acc)[2][2][4][2], const Unit& u, int wr, int wc, int fr, int fq) const {
;     ...
;         for (int mh = 0; mh < 2; ++mh) {
;             f32x4 bf[2][2][2]; u32x4 bh[2][2];
; #pragma unroll
;             for (int m2 = 0; m2 < 2; ++m2)
; #pragma unroll
;                 for (int bj = 0; bj < 2; ++bj) {
;                     const size_t off = (size_t)(u.pm * BM + ai * HALF + wr * 64 + (2 * mh + m2) * 16 + fr) * 1024 + col0 + bj * HALF;
;                     if (!basef) bh[m2][bj] = *(const u32x4*)(xin + off);
;                 }
; #pragma unroll
;             for (int m2 = 0; m2 < 2; ++m2) {
;                 const int m = 2 * mh + m2;
;                 const int row = u.pm * BM + ai * HALF + wr * 64 + m * 16 + fr; float sq = 0.f;
;                 if (basef) {
; #pragma unroll
;                     for (int bj = 0; bj < 2; ++bj) { const size_t off = (size_t)row * 1024 + col0 + bj * HALF; bf[m2][bj][0] = *(const f32x4*)(basef + off); bf[m2][bj][1] = *(const f32x4*)(basef + off + 4); }
;                 }
; #pragma unroll
;                 for (int bj = 0; bj < 2; ++bj) {
;                     const size_t off = (size_t)row * 1024 + col0 + bj * HALF;
;                     float bv[8];
;                     if (basef) { const f32x4 b0 = bf[m2][bj][0], b1 = bf[m2][bj][1]; bv[0] = b0[0]; bv[1] = b0[1]; bv[2] = b0[2]; bv[3] = b0[3]; bv[4] = b1[0]; bv[5] = b1[1]; bv[6] = b1[2]; bv[7] = b1[3]; }
;                     else { const u32x4 gw = bh[m2][bj];
;                         bv[0] = __uint_as_float(gw.x << 16); bv[1] = __uint_as_float(gw.x & 0xffff0000u); bv[2] = __uint_as_float(gw.y << 16); bv[3] = __uint_as_float(gw.y & 0xffff0000u);
;                         bv[4] = __uint_as_float(gw.z << 16); bv[5] = __uint_as_float(gw.z & 0xffff0000u); bv[6] = __uint_as_float(gw.w << 16); bv[7] = __uint_as_float(gw.w & 0xffff0000u); }
;                     float y[8];
; #pragma unroll
;                     for (int e = 0; e < 4; ++e) { y[e] = bv[e] + alpha * acc[ai][bj][m][0][e]; y[4 + e] = bv[4 + e] + alpha * acc[ai][bj][m][1][e]; }
;                     u32x4 w; w.x = cvt_pk_bf16(y[0], y[1]); w.y = cvt_pk_bf16(y[2], y[3]); w.z = cvt_pk_bf16(y[4], y[5]); w.w = cvt_pk_bf16(y[6], y[7]);
;                     *(u32x4*)(xs + off) = w;
	v_fmac_f32_e32 v0, 0.5, v112
	v_fmac_f32_e32 v1, 0.5, v113
	v_fmac_f32_e32 v2, 0.5, v114
	v_fmac_f32_e32 v3, 0.5, v115
	v_fmac_f32_e32 v4, 0.5, v108
	v_fmac_f32_e32 v5, 0.5, v109
	v_fmac_f32_e32 v6, 0.5, v110
	v_fmac_f32_e32 v7, 0.5, v111
	v_fmac_f32_e32 v8, 0.5, v100
	v_fmac_f32_e32 v9, 0.5, v101
	v_fmac_f32_e32 v10, 0.5, v102
	v_fmac_f32_e32 v11, 0.5, v103
	v_fmac_f32_e32 v12, 0.5, v96
	v_fmac_f32_e32 v13, 0.5, v97
	v_fmac_f32_e32 v14, 0.5, v98
	v_fmac_f32_e32 v15, 0.5, v99
	v_mul_f32_e32 v108, v0, v0
	v_mul_f32_e32 v109, v2, v2
	v_mul_f32_e32 v110, v4, v4
	v_mul_f32_e32 v111, v6, v6
	v_fmac_f32_e32 v108, v1, v1
	v_fmac_f32_e32 v109, v3, v3
	v_fmac_f32_e32 v110, v5, v5
	v_fmac_f32_e32 v111, v7, v7
	v_add_f32_e32 v108, v108, v109
	v_add_f32_e32 v110, v110, v111
	v_add_f32_e32 v108, v108, v110
	v_mul_f32_e32 v96, v8, v8
	v_mul_f32_e32 v97, v10, v10
	v_mul_f32_e32 v98, v12, v12
	v_mul_f32_e32 v99, v14, v14
	v_fmac_f32_e32 v96, v9, v9
	v_fmac_f32_e32 v97, v11, v11
	v_fmac_f32_e32 v98, v13, v13
	v_fmac_f32_e32 v99, v15, v15
	v_add_f32_e32 v96, v96, v97
	v_add_f32_e32 v98, v98, v99
	v_add_f32_e32 v96, v96, v98
	v_add_f32_e32 v244, v108, v96
	v_mov_b32_e32 v245, v244
	s_nop 1
	v_permlane16_swap_b32_e32 v244, v245
	s_mov_b32 s98, 0x40000
	v_lshl_add_u64 v[240:241], v[236:237], 0, s[98:99]
	v_cvt_pk_bf16_f32 v112, v0, v1
	v_cvt_pk_bf16_f32 v113, v2, v3
	v_cvt_pk_bf16_f32 v114, v4, v5
	v_cvt_pk_bf16_f32 v115, v6, v7
	global_store_dwordx4 v[240:241], v[112:115], off
	v_cvt_pk_bf16_f32 v100, v8, v9
	v_cvt_pk_bf16_f32 v101, v10, v11
	v_cvt_pk_bf16_f32 v102, v12, v13
	v_cvt_pk_bf16_f32 v103, v14, v15
	global_store_dwordx4 v[240:241], v[100:103], off offset:256
	s_waitcnt lgkmcnt(0)
	v_add_f32_e32 v244, v244, v245
	v_mov_b32_e32 v245, v244
	s_nop 1
	v_permlane32_swap_b32_e32 v244, v245
	s_mov_b32 s98, 0x2000
	v_lshl_add_u64 v[240:241], v[238:239], 0, s[98:99]
	s_waitcnt lgkmcnt(0)
	v_add_f32_e32 v244, v244, v245
	s_and_saveexec_b64 s[50:51], s[8:9]
	global_store_dword v[240:241], v244, off
	s_mov_b64 exec, s[50:51]
	s_waitcnt vmcnt(17)
	v_fmac_f32_e32 v16, 0.5, v92
	v_fmac_f32_e32 v17, 0.5, v93
	v_fmac_f32_e32 v18, 0.5, v94
	v_fmac_f32_e32 v19, 0.5, v95
	v_fmac_f32_e32 v20, 0.5, v88
	v_fmac_f32_e32 v21, 0.5, v89
	v_fmac_f32_e32 v22, 0.5, v90
	v_fmac_f32_e32 v23, 0.5, v91
	v_fmac_f32_e32 v104, 0.5, v84
	v_fmac_f32_e32 v105, 0.5, v85
	v_fmac_f32_e32 v106, 0.5, v86
	v_fmac_f32_e32 v107, 0.5, v87
	v_fmac_f32_e32 v116, 0.5, v80
	v_fmac_f32_e32 v117, 0.5, v81
	v_fmac_f32_e32 v118, 0.5, v82
	v_fmac_f32_e32 v119, 0.5, v83
	v_mul_f32_e32 v88, v16, v16
	v_mul_f32_e32 v89, v18, v18
	v_mul_f32_e32 v90, v20, v20
	v_mul_f32_e32 v91, v22, v22
	v_fmac_f32_e32 v88, v17, v17
	v_fmac_f32_e32 v89, v19, v19
	v_fmac_f32_e32 v90, v21, v21
	v_fmac_f32_e32 v91, v23, v23
	v_add_f32_e32 v88, v88, v89
	v_add_f32_e32 v90, v90, v91
	v_add_f32_e32 v88, v88, v90
	v_mul_f32_e32 v80, v104, v104
	v_mul_f32_e32 v81, v106, v106
	v_mul_f32_e32 v82, v116, v116
	v_mul_f32_e32 v83, v118, v118
	v_fmac_f32_e32 v80, v105, v105
	v_fmac_f32_e32 v81, v107, v107
	v_fmac_f32_e32 v82, v117, v117
	v_fmac_f32_e32 v83, v119, v119
	v_add_f32_e32 v80, v80, v81
	v_add_f32_e32 v82, v82, v83
	v_add_f32_e32 v80, v80, v82
	v_add_f32_e32 v244, v88, v80
	v_mov_b32_e32 v245, v244
	s_nop 1
	v_permlane16_swap_b32_e32 v244, v245
	s_mov_b32 s98, 0x48000
	v_lshl_add_u64 v[240:241], v[236:237], 0, s[98:99]
	v_cvt_pk_bf16_f32 v92, v16, v17
	v_cvt_pk_bf16_f32 v93, v18, v19
	v_cvt_pk_bf16_f32 v94, v20, v21
	v_cvt_pk_bf16_f32 v95, v22, v23
	global_store_dwordx4 v[240:241], v[92:95], off
	v_cvt_pk_bf16_f32 v84, v104, v105
	v_cvt_pk_bf16_f32 v85, v106, v107
	v_cvt_pk_bf16_f32 v86, v116, v117
	v_cvt_pk_bf16_f32 v87, v118, v119
	global_store_dwordx4 v[240:241], v[84:87], off offset:256
	s_waitcnt lgkmcnt(0)
	v_add_f32_e32 v244, v244, v245
	v_mov_b32_e32 v245, v244
	s_nop 1
	v_permlane32_swap_b32_e32 v244, v245
	s_mov_b32 s98, 0x2400
	v_lshl_add_u64 v[240:241], v[238:239], 0, s[98:99]
	s_waitcnt lgkmcnt(0)
	v_add_f32_e32 v244, v244, v245
	s_and_saveexec_b64 s[50:51], s[8:9]
	global_store_dword v[240:241], v244, off
	s_mov_b64 exec, s[50:51]
	s_waitcnt vmcnt(13)
;     __device__ __forceinline__ void operator()(const f32x4 (&acc)[2][2][4][2], const Unit& u, int wr, int wc, int fr, int fq) const {
;     ...
;         for (int mh = 0; mh < 2; ++mh) {
;             f32x4 bf[2][2][2]; u32x4 bh[2][2];
; #pragma unroll
;             for (int m2 = 0; m2 < 2; ++m2)
; #pragma unroll
;                 for (int bj = 0; bj < 2; ++bj) {
;                     const size_t off = (size_t)(u.pm * BM + ai * HALF + wr * 64 + (2 * mh + m2) * 16 + fr) * 1024 + col0 + bj * HALF;
;                     if (!basef) bh[m2][bj] = *(const u32x4*)(xin + off);
;                 }
; #pragma unroll
;             for (int m2 = 0; m2 < 2; ++m2) {
;                 const int m = 2 * mh + m2;
;                 const int row = u.pm * BM + ai * HALF + wr * 64 + m * 16 + fr; float sq = 0.f;
;                 if (basef) {
; #pragma unroll
;                     for (int bj = 0; bj < 2; ++bj) { const size_t off = (size_t)row * 1024 + col0 + bj * HALF; bf[m2][bj][0] = *(const f32x4*)(basef + off); bf[m2][bj][1] = *(const f32x4*)(basef + off + 4); }
;                 }
; #pragma unroll
;                 for (int bj = 0; bj < 2; ++bj) {
;                     const size_t off = (size_t)row * 1024 + col0 + bj * HALF;
;                     float bv[8];
;                     if (basef) { const f32x4 b0 = bf[m2][bj][0], b1 = bf[m2][bj][1]; bv[0] = b0[0]; bv[1] = b0[1]; bv[2] = b0[2]; bv[3] = b0[3]; bv[4] = b1[0]; bv[5] = b1[1]; bv[6] = b1[2]; bv[7] = b1[3]; }
;                     else { const u32x4 gw = bh[m2][bj];
;                         bv[0] = __uint_as_float(gw.x << 16); bv[1] = __uint_as_float(gw.x & 0xffff0000u); bv[2] = __uint_as_float(gw.y << 16); bv[3] = __uint_as_float(gw.y & 0xffff0000u);
;                         bv[4] = __uint_as_float(gw.z << 16); bv[5] = __uint_as_float(gw.z & 0xffff0000u); bv[6] = __uint_as_float(gw.w << 16); bv[7] = __uint_as_float(gw.w & 0xffff0000u); }
;                     float y[8];
; #pragma unroll
;                     for (int e = 0; e < 4; ++e) { y[e] = bv[e] + alpha * acc[ai][bj][m][0][e]; y[4 + e] = bv[4 + e] + alpha * acc[ai][bj][m][1][e]; }
;                     u32x4 w; w.x = cvt_pk_bf16(y[0], y[1]); w.y = cvt_pk_bf16(y[2], y[3]); w.z = cvt_pk_bf16(y[4], y[5]); w.w = cvt_pk_bf16(y[6], y[7]);
;                     *(u32x4*)(xs + off) = w;
	v_fmac_f32_e32 v184, 0.5, v76
	v_fmac_f32_e32 v185, 0.5, v77
	v_fmac_f32_e32 v186, 0.5, v78
	v_fmac_f32_e32 v187, 0.5, v79
	v_fmac_f32_e32 v188, 0.5, v72
	v_fmac_f32_e32 v189, 0.5, v73
	v_fmac_f32_e32 v190, 0.5, v74
	v_fmac_f32_e32 v191, 0.5, v75
	v_fmac_f32_e32 v192, 0.5, v68
	v_fmac_f32_e32 v193, 0.5, v69
	v_fmac_f32_e32 v194, 0.5, v70
	v_fmac_f32_e32 v195, 0.5, v71
	v_fmac_f32_e32 v206, 0.5, v64
	v_fmac_f32_e32 v207, 0.5, v65
	v_fmac_f32_e32 v208, 0.5, v66
	v_fmac_f32_e32 v209, 0.5, v67
	v_mul_f32_e32 v72, v184, v184
	v_mul_f32_e32 v73, v186, v186
	v_mul_f32_e32 v74, v188, v188
	v_mul_f32_e32 v75, v190, v190
	v_fmac_f32_e32 v72, v185, v185
	v_fmac_f32_e32 v73, v187, v187
	v_fmac_f32_e32 v74, v189, v189
	v_fmac_f32_e32 v75, v191, v191
	v_add_f32_e32 v72, v72, v73
	v_add_f32_e32 v74, v74, v75
	v_add_f32_e32 v72, v72, v74
	v_mul_f32_e32 v64, v192, v192
	v_mul_f32_e32 v65, v194, v194
	v_mul_f32_e32 v66, v206, v206
	v_mul_f32_e32 v67, v208, v208
	v_fmac_f32_e32 v64, v193, v193
	v_fmac_f32_e32 v65, v195, v195
	v_fmac_f32_e32 v66, v207, v207
	v_fmac_f32_e32 v67, v209, v209
	v_add_f32_e32 v64, v64, v65
	v_add_f32_e32 v66, v66, v67
	v_add_f32_e32 v64, v64, v66
	v_add_f32_e32 v244, v72, v64
	v_mov_b32_e32 v245, v244
	s_nop 1
	v_permlane16_swap_b32_e32 v244, v245
	s_mov_b32 s98, 0x50000
	v_lshl_add_u64 v[240:241], v[236:237], 0, s[98:99]
	v_cvt_pk_bf16_f32 v76, v184, v185
	v_cvt_pk_bf16_f32 v77, v186, v187
	v_cvt_pk_bf16_f32 v78, v188, v189
	v_cvt_pk_bf16_f32 v79, v190, v191
	global_store_dwordx4 v[240:241], v[76:79], off
	v_cvt_pk_bf16_f32 v68, v192, v193
	v_cvt_pk_bf16_f32 v69, v194, v195
	v_cvt_pk_bf16_f32 v70, v206, v207
	v_cvt_pk_bf16_f32 v71, v208, v209
	global_store_dwordx4 v[240:241], v[68:71], off offset:256
	s_waitcnt lgkmcnt(0)
	v_add_f32_e32 v244, v244, v245
	v_mov_b32_e32 v245, v244
	s_nop 1
	v_permlane32_swap_b32_e32 v244, v245
	s_mov_b32 s98, 0x2800
	v_lshl_add_u64 v[240:241], v[238:239], 0, s[98:99]
	s_waitcnt lgkmcnt(0)
	v_add_f32_e32 v244, v244, v245
	s_and_saveexec_b64 s[50:51], s[8:9]
	global_store_dword v[240:241], v244, off
	s_mov_b64 exec, s[50:51]
	s_waitcnt vmcnt(9)
	v_fmac_f32_e32 v210, 0.5, v60
	v_fmac_f32_e32 v211, 0.5, v61
	v_fmac_f32_e32 v212, 0.5, v62
	v_fmac_f32_e32 v213, 0.5, v63
	v_fmac_f32_e32 v214, 0.5, v56
	v_fmac_f32_e32 v215, 0.5, v57
	v_fmac_f32_e32 v216, 0.5, v58
	v_fmac_f32_e32 v217, 0.5, v59
	v_fmac_f32_e32 v132, 0.5, v52
	v_fmac_f32_e32 v133, 0.5, v53
	v_fmac_f32_e32 v134, 0.5, v54
	v_fmac_f32_e32 v135, 0.5, v55
	v_fmac_f32_e32 v124, 0.5, v48
	v_fmac_f32_e32 v125, 0.5, v49
	v_fmac_f32_e32 v126, 0.5, v50
	v_fmac_f32_e32 v127, 0.5, v51
	v_mul_f32_e32 v56, v210, v210
	v_mul_f32_e32 v57, v212, v212
	v_mul_f32_e32 v58, v214, v214
	v_mul_f32_e32 v59, v216, v216
	v_fmac_f32_e32 v56, v211, v211
	v_fmac_f32_e32 v57, v213, v213
	v_fmac_f32_e32 v58, v215, v215
	v_fmac_f32_e32 v59, v217, v217
	v_add_f32_e32 v56, v56, v57
	v_add_f32_e32 v58, v58, v59
	v_add_f32_e32 v56, v56, v58
	v_mul_f32_e32 v48, v132, v132
	v_mul_f32_e32 v49, v134, v134
	v_mul_f32_e32 v50, v124, v124
	v_mul_f32_e32 v51, v126, v126
	v_fmac_f32_e32 v48, v133, v133
	v_fmac_f32_e32 v49, v135, v135
	v_fmac_f32_e32 v50, v125, v125
	v_fmac_f32_e32 v51, v127, v127
	v_add_f32_e32 v48, v48, v49
	v_add_f32_e32 v50, v50, v51
	v_add_f32_e32 v48, v48, v50
	v_add_f32_e32 v244, v56, v48
	v_mov_b32_e32 v245, v244
	s_nop 1
	v_permlane16_swap_b32_e32 v244, v245
	s_mov_b32 s98, 0x58000
	v_lshl_add_u64 v[240:241], v[236:237], 0, s[98:99]
	v_cvt_pk_bf16_f32 v60, v210, v211
	v_cvt_pk_bf16_f32 v61, v212, v213
	v_cvt_pk_bf16_f32 v62, v214, v215
	v_cvt_pk_bf16_f32 v63, v216, v217
	global_store_dwordx4 v[240:241], v[60:63], off
	v_cvt_pk_bf16_f32 v52, v132, v133
	v_cvt_pk_bf16_f32 v53, v134, v135
	v_cvt_pk_bf16_f32 v54, v124, v125
	v_cvt_pk_bf16_f32 v55, v126, v127
	global_store_dwordx4 v[240:241], v[52:55], off offset:256
	s_waitcnt lgkmcnt(0)
	v_add_f32_e32 v244, v244, v245
	v_mov_b32_e32 v245, v244
	s_nop 1
	v_permlane32_swap_b32_e32 v244, v245
	s_mov_b32 s98, 0x2c00
	v_lshl_add_u64 v[240:241], v[238:239], 0, s[98:99]
	s_waitcnt lgkmcnt(0)
	v_add_f32_e32 v244, v244, v245
	s_and_saveexec_b64 s[50:51], s[8:9]
	global_store_dword v[240:241], v244, off
	s_mov_b64 exec, s[50:51]
	s_branch .Lp2_epi_done
